# combo15: combo14 + adaLN silu staging loop unrolled (8 loads in flight instead of one load per iteration with a full wait)
# baseline (speedup 1.0000x reference)
; #define LAS __attribute__((address_space(3)))
; __device__ __forceinline__ int opaque_tid() { int t = threadIdx.x; asm volatile("" : "+v"(t)); return t; }
; __device__ __forceinline__ void adaln_unit(int u, const float* c, const float* w_ada, const float* b_ada, float* mod, LAS float* lds) {
;     const int tid = opaque_tid(), wave = tid >> 6, lane = tid & 63;
;     const int l = u / 96, n0 = (u % 96) * 64;
;     LAS float* sc = lds; LAS float* red = lds + 4096;
;     for (int i = tid; i < 4096; i += 512) { const float v = c[i]; sc[i] = v / (1.0f + __expf(-v)); }
;     __syncthreads();
.LBB0_12:
	global_load_dword v24, v[6:7], off
	global_load_dword v25, v[6:7], off offset:2048
	v_add_co_u32_e32 v32, vcc, 0x1000, v6
	v_addc_co_u32_e32 v33, vcc, 0, v7, vcc
	global_load_dword v26, v[32:33], off
	global_load_dword v27, v[32:33], off offset:2048
	v_add_co_u32_e32 v32, vcc, 0x2000, v6
	v_addc_co_u32_e32 v33, vcc, 0, v7, vcc
	global_load_dword v28, v[32:33], off
	global_load_dword v29, v[32:33], off offset:2048
	v_add_co_u32_e32 v32, vcc, 0x3000, v6
	v_addc_co_u32_e32 v33, vcc, 0, v7, vcc
	global_load_dword v30, v[32:33], off
	global_load_dword v31, v[32:33], off offset:2048
	s_waitcnt vmcnt(7)
	v_mul_f32_e32 v10, 0xbfb8aa3b, v24
	v_exp_f32_e32 v10, v10
	s_nop 0
	v_add_f32_e32 v10, 1.0, v10
	v_div_scale_f32 v11, s[20:21], v10, v10, v24
	v_rcp_f32_e32 v12, v11
	v_div_scale_f32 v13, vcc, v24, v10, v24
	v_fma_f32 v14, -v11, v12, 1.0
	v_fmac_f32_e32 v12, v14, v12
	v_mul_f32_e32 v14, v13, v12
	v_fma_f32 v15, -v11, v14, v13
	v_fmac_f32_e32 v14, v15, v12
	v_fma_f32 v11, -v11, v14, v13
	v_div_fmas_f32 v11, v11, v12, v14
	v_div_fixup_f32 v5, v11, v10, v24
	ds_write_b32 v9, v5 offset:0
	s_waitcnt vmcnt(6)
	v_mul_f32_e32 v10, 0xbfb8aa3b, v25
	v_exp_f32_e32 v10, v10
	s_nop 0
	v_add_f32_e32 v10, 1.0, v10
	v_div_scale_f32 v11, s[20:21], v10, v10, v25
	v_rcp_f32_e32 v12, v11
	v_div_scale_f32 v13, vcc, v25, v10, v25
	v_fma_f32 v14, -v11, v12, 1.0
	v_fmac_f32_e32 v12, v14, v12
	v_mul_f32_e32 v14, v13, v12
	v_fma_f32 v15, -v11, v14, v13
	v_fmac_f32_e32 v14, v15, v12
	v_fma_f32 v11, -v11, v14, v13
	v_div_fmas_f32 v11, v11, v12, v14
	v_div_fixup_f32 v5, v11, v10, v25
	ds_write_b32 v9, v5 offset:2048
	s_waitcnt vmcnt(5)
	v_mul_f32_e32 v10, 0xbfb8aa3b, v26
	v_exp_f32_e32 v10, v10
	s_nop 0
	v_add_f32_e32 v10, 1.0, v10
	v_div_scale_f32 v11, s[20:21], v10, v10, v26
	v_rcp_f32_e32 v12, v11
	v_div_scale_f32 v13, vcc, v26, v10, v26
	v_fma_f32 v14, -v11, v12, 1.0
	v_fmac_f32_e32 v12, v14, v12
	v_mul_f32_e32 v14, v13, v12
	v_fma_f32 v15, -v11, v14, v13
	v_fmac_f32_e32 v14, v15, v12
	v_fma_f32 v11, -v11, v14, v13
	v_div_fmas_f32 v11, v11, v12, v14
	v_div_fixup_f32 v5, v11, v10, v26
	ds_write_b32 v9, v5 offset:4096
	s_waitcnt vmcnt(4)
	v_mul_f32_e32 v10, 0xbfb8aa3b, v27
	v_exp_f32_e32 v10, v10
	s_nop 0
	v_add_f32_e32 v10, 1.0, v10
	v_div_scale_f32 v11, s[20:21], v10, v10, v27
	v_rcp_f32_e32 v12, v11
	v_div_scale_f32 v13, vcc, v27, v10, v27
	v_fma_f32 v14, -v11, v12, 1.0
	v_fmac_f32_e32 v12, v14, v12
	v_mul_f32_e32 v14, v13, v12
	v_fma_f32 v15, -v11, v14, v13
	v_fmac_f32_e32 v14, v15, v12
	v_fma_f32 v11, -v11, v14, v13
	v_div_fmas_f32 v11, v11, v12, v14
	v_div_fixup_f32 v5, v11, v10, v27
	ds_write_b32 v9, v5 offset:6144
	s_waitcnt vmcnt(3)
	v_mul_f32_e32 v10, 0xbfb8aa3b, v28
	v_exp_f32_e32 v10, v10
	s_nop 0
	v_add_f32_e32 v10, 1.0, v10
	v_div_scale_f32 v11, s[20:21], v10, v10, v28
	v_rcp_f32_e32 v12, v11
	v_div_scale_f32 v13, vcc, v28, v10, v28
	v_fma_f32 v14, -v11, v12, 1.0
	v_fmac_f32_e32 v12, v14, v12
	v_mul_f32_e32 v14, v13, v12
	v_fma_f32 v15, -v11, v14, v13
	v_fmac_f32_e32 v14, v15, v12
	v_fma_f32 v11, -v11, v14, v13
	v_div_fmas_f32 v11, v11, v12, v14
	v_div_fixup_f32 v5, v11, v10, v28
	ds_write_b32 v9, v5 offset:8192
	s_waitcnt vmcnt(2)
	v_mul_f32_e32 v10, 0xbfb8aa3b, v29
	v_exp_f32_e32 v10, v10
	s_nop 0
	v_add_f32_e32 v10, 1.0, v10
	v_div_scale_f32 v11, s[20:21], v10, v10, v29
	v_rcp_f32_e32 v12, v11
	v_div_scale_f32 v13, vcc, v29, v10, v29
	v_fma_f32 v14, -v11, v12, 1.0
	v_fmac_f32_e32 v12, v14, v12
	v_mul_f32_e32 v14, v13, v12
	v_fma_f32 v15, -v11, v14, v13
	v_fmac_f32_e32 v14, v15, v12
	v_fma_f32 v11, -v11, v14, v13
	v_div_fmas_f32 v11, v11, v12, v14
	v_div_fixup_f32 v5, v11, v10, v29
	ds_write_b32 v9, v5 offset:10240
	s_waitcnt vmcnt(1)
	v_mul_f32_e32 v10, 0xbfb8aa3b, v30
	v_exp_f32_e32 v10, v10
	s_nop 0
	v_add_f32_e32 v10, 1.0, v10
	v_div_scale_f32 v11, s[20:21], v10, v10, v30
	v_rcp_f32_e32 v12, v11
	v_div_scale_f32 v13, vcc, v30, v10, v30
	v_fma_f32 v14, -v11, v12, 1.0
	v_fmac_f32_e32 v12, v14, v12
	v_mul_f32_e32 v14, v13, v12
	v_fma_f32 v15, -v11, v14, v13
	v_fmac_f32_e32 v14, v15, v12
	v_fma_f32 v11, -v11, v14, v13
	v_div_fmas_f32 v11, v11, v12, v14
	v_div_fixup_f32 v5, v11, v10, v30
	ds_write_b32 v9, v5 offset:12288
	s_waitcnt vmcnt(0)
	v_mul_f32_e32 v10, 0xbfb8aa3b, v31
	v_exp_f32_e32 v10, v10
	s_nop 0
	v_add_f32_e32 v10, 1.0, v10
	v_div_scale_f32 v11, s[20:21], v10, v10, v31
	v_rcp_f32_e32 v12, v11
	v_div_scale_f32 v13, vcc, v31, v10, v31
	v_fma_f32 v14, -v11, v12, 1.0
	v_fmac_f32_e32 v12, v14, v12
	v_mul_f32_e32 v14, v13, v12
	v_fma_f32 v15, -v11, v14, v13
	v_fmac_f32_e32 v14, v15, v12
	v_fma_f32 v11, -v11, v14, v13
	v_div_fmas_f32 v11, v11, v12, v14
	v_div_fixup_f32 v5, v11, v10, v31
	ds_write_b32 v9, v5 offset:14336
	s_or_b64 exec, exec, s[8:9]
